# phase_weights wave-to-item mapping reversed so the workgroups with a second modulation item get 10 instead of 11 weight items
# baseline (speedup 1.0000x reference)
.LBB0_18:
	v_mov_b32_e32 v2, v128
	s_lshl_b32 s2, s59, 3
	v_writelane_b32 v251, s2, 14
	v_ashrrev_i32_e32 v3, 6, v2
	v_add_u32_e32 v1, s2, v3
	v_sub_u32_e32 v1, 0x7ff, v1
	v_readlane_b32 s2, v251, 0
	s_movk_i32 s33, 0x5180
	v_readlane_b32 s3, v251, 1
	s_lshl_b32 s64, s2, 3
	v_cmp_gt_i32_e32 vcc, s33, v1
	s_and_saveexec_b64 s[2:3], vcc
	s_cbranch_execz .LBB0_69
	s_movk_i32 s4, 0x2200
	v_mul_lo_u32 v3, v3, s4
	v_readlane_b32 s4, v251, 0
	v_readlane_b32 s8, v251, 2
	v_readlane_b32 s5, v251, 1
	v_readlane_b32 s9, v251, 3
	s_lshl_b32 s46, s4, 4
	s_load_dwordx4 s[20:23], s[8:9], 0xb8
	s_load_dwordx4 s[4:7], s[8:9], 0xd0
	s_load_dwordx8 s[12:19], s[8:9], 0x70
	v_add_u32_e32 v3, 0, v3
	v_bfe_u32 v84, v2, 3, 3
	v_lshlrev_b32_e32 v4, 2, v2
	s_waitcnt lgkmcnt(0)
	s_add_u32 s10, s6, 0x5080000
	s_addc_u32 s11, s7, 0
	s_add_u32 s24, s6, 0x4a80000
	s_addc_u32 s25, s7, 0
	s_add_u32 s26, s6, 0x4880000
	s_addc_u32 s27, s7, 0
	s_add_u32 s28, s6, 0x4300000
	s_addc_u32 s29, s7, 0
	s_add_u32 s30, s6, 0x2d00000
	v_and_b32_e32 v5, 7, v2
	s_addc_u32 s31, s7, 0
	v_and_b32_e32 v4, 28, v4
	v_lshl_add_u32 v6, v5, 4, v3
	v_mul_u32_u24_e32 v7, 0x84, v84
	v_lshlrev_b32_e32 v2, 3, v5
	v_mul_u32_u24_e32 v5, 0x420, v5
	v_lshlrev_b32_e32 v8, 2, v84
	s_add_u32 s34, s6, 0x100000
	v_mov_b32_e32 v67, 0
	v_or_b32_e32 v85, 8, v84
	v_or_b32_e32 v86, 16, v84
	v_or_b32_e32 v87, 24, v84
	v_add3_u32 v88, v3, v5, v8
	s_addc_u32 s35, s7, 0
	s_mov_b64 s[36:37], 0
	s_movk_i32 s47, 0x2c00
	s_movk_i32 s48, 0x2bff
	s_movk_i32 s49, 0x41ff
	s_movk_i32 s50, 0x477f
	s_movk_i32 s51, 0x497f
	s_movk_i32 s52, 0x4f7f
	s_mov_b32 s53, 0xb00000
	s_mov_b32 s54, 0x580000
	s_mov_b32 s55, 0x2e8ba2e9
	s_mov_b32 s56, 0x1600000
	v_lshlrev_b32_e32 v66, 2, v4
	s_movk_i32 s57, 0xba3
	v_lshlrev_b32_e32 v68, 1, v2
	s_movk_i32 s58, 0x517f
	v_mov_b32_e32 v89, 30
	v_mov_b32_e32 v90, 6
	v_mov_b32_e32 v91, 5
	v_add_u32_e32 v92, v6, v7
	v_mov_b32_e32 v93, 8
	v_mov_b32_e32 v94, 7
	s_branch .LBB0_22
